# v17: v15 + int8 GEMM epilogue: all per-row step loads issued before the stores (no load waits behind store acks)
# speedup vs baseline: 1.0007x; 1.0007x over previous
.LBB0_312:
	v_lshl_or_b32 v160, s47, 8, v168
	v_lshl_add_u32 v162, s46, 7, v97
	v_ashrrev_i32_e32 v161, 31, v160
	v_ashrrev_i32_e32 v163, 31, v162
	v_lshl_add_u64 v[60:61], v[160:161], 2, s[12:13]
	v_lshl_add_u64 v[164:165], v[162:163], 2, s[10:11]
	global_load_dwordx4 v[68:71], v[60:61], off offset:16
	global_load_dwordx4 v[72:75], v[60:61], off
	global_load_dwordx4 v[56:59], v[60:61], off offset:528
	s_nop 0
	global_load_dwordx4 v[60:63], v[60:61], off offset:512
	v_cvt_f32_i32_e32 v143, v143
	global_load_dword v170, v[164:165], off
	global_load_dword v166, v[164:165], off offset:64
	global_load_dword v178, v[164:165], off offset:128
	global_load_dword v179, v[164:165], off offset:192
	global_load_dword v180, v[164:165], off offset:512
	global_load_dword v181, v[164:165], off offset:576
	global_load_dword v182, v[164:165], off offset:640
	global_load_dword v183, v[164:165], off offset:704
	v_cvt_f32_i32_e32 v142, v142
	v_cvt_f32_i32_e32 v145, v145
	v_cvt_f32_i32_e32 v144, v144
	v_cvt_f32_i32_e32 v139, v139
	v_cvt_f32_i32_e32 v138, v138
	v_cvt_f32_i32_e32 v141, v141
	v_cvt_f32_i32_e32 v140, v140
	v_mov_b64_e32 v[158:159], s[8:9]
	v_cvt_f32_i32_e32 v135, v135
	v_cvt_f32_i32_e32 v134, v134
	v_cvt_f32_i32_e32 v137, v137
	v_cvt_f32_i32_e32 v136, v136
	v_mad_i64_i32 v[172:173], s[26:27], v162, s21, v[158:159]
	v_lshlrev_b64 v[160:161], 1, v[160:161]
	v_cvt_f32_i32_e32 v131, v131
	v_cvt_f32_i32_e32 v130, v130
	v_cvt_f32_i32_e32 v133, v133
	v_cvt_f32_i32_e32 v132, v132
	v_lshl_add_u64 v[172:173], v[172:173], 0, v[160:161]
	v_cvt_f32_i32_e32 v127, v127
	v_cvt_f32_i32_e32 v126, v126
	v_cvt_f32_i32_e32 v129, v129
	v_cvt_f32_i32_e32 v128, v128
	v_cvt_f32_i32_e32 v123, v123
	v_cvt_f32_i32_e32 v122, v122
	v_cvt_f32_i32_e32 v125, v125
	v_cvt_f32_i32_e32 v124, v124
	v_cvt_f32_i32_e32 v119, v119
	v_cvt_f32_i32_e32 v118, v118
	v_cvt_f32_i32_e32 v121, v121
	v_cvt_f32_i32_e32 v120, v120
	v_cvt_f32_i32_e32 v115, v115
	v_cvt_f32_i32_e32 v114, v114
	v_cvt_f32_i32_e32 v117, v117
	v_cvt_f32_i32_e32 v116, v116
	v_cvt_f32_i32_e32 v111, v111
	v_cvt_f32_i32_e32 v110, v110
	v_cvt_f32_i32_e32 v113, v113
	v_cvt_f32_i32_e32 v112, v112
	v_cvt_f32_i32_e32 v107, v107
	v_cvt_f32_i32_e32 v106, v106
	v_cvt_f32_i32_e32 v109, v109
	v_cvt_f32_i32_e32 v108, v108
	v_cvt_f32_i32_e32 v103, v103
	v_cvt_f32_i32_e32 v102, v102
	v_cvt_f32_i32_e32 v105, v105
	v_cvt_f32_i32_e32 v104, v104
	v_cvt_f32_i32_e32 v99, v99
	v_cvt_f32_i32_e32 v98, v98
	v_cvt_f32_i32_e32 v101, v101
	v_cvt_f32_i32_e32 v100, v100
	v_cvt_f32_i32_e32 v93, v93
	v_cvt_f32_i32_e32 v92, v92
	v_cvt_f32_i32_e32 v95, v95
	v_cvt_f32_i32_e32 v94, v94
	v_cvt_f32_i32_e32 v89, v89
	v_cvt_f32_i32_e32 v88, v88
	v_cvt_f32_i32_e32 v91, v91
	v_cvt_f32_i32_e32 v90, v90
	v_cvt_f32_i32_e32 v85, v85
	v_cvt_f32_i32_e32 v84, v84
	v_cvt_f32_i32_e32 v87, v87
	v_cvt_f32_i32_e32 v86, v86
	v_cvt_f32_i32_e32 v81, v81
	v_cvt_f32_i32_e32 v80, v80
	v_cvt_f32_i32_e32 v83, v83
	v_cvt_f32_i32_e32 v82, v82
	v_cvt_f32_i32_e32 v77, v77
	v_cvt_f32_i32_e32 v76, v76
	v_cvt_f32_i32_e32 v79, v79
	v_cvt_f32_i32_e32 v78, v78
	v_cvt_f32_i32_e32 v65, v65
	v_cvt_f32_i32_e32 v64, v64
	v_cvt_f32_i32_e32 v67, v67
	v_cvt_f32_i32_e32 v66, v66
	v_cvt_f32_i32_e32 v53, v53
	v_cvt_f32_i32_e32 v52, v52
	s_waitcnt vmcnt(0)
	v_pk_mul_f32 v[174:175], v[72:73], v[170:171] op_sel_hi:[1,0]
	v_pk_mul_f32 v[176:177], v[74:75], v[170:171] op_sel_hi:[1,0]
	v_pk_mul_f32 v[142:143], v[174:175], v[142:143]
	v_pk_mul_f32 v[144:145], v[176:177], v[144:145]
	v_pk_mul_f32 v[174:175], v[68:69], v[170:171] op_sel_hi:[1,0]
	v_pk_mul_f32 v[176:177], v[70:71], v[170:171] op_sel_hi:[1,0]
	v_cvt_f32_i32_e32 v55, v55
	v_pk_mul_f32 v[176:177], v[176:177], v[140:141]
	v_pk_mul_f32 v[140:141], v[174:175], v[138:139]
	v_cvt_pk_bf16_f32 v138, v142, v143
	v_cvt_pk_bf16_f32 v139, v144, v145
	v_cvt_f32_i32_e32 v54, v54
	v_cvt_pk_bf16_f32 v140, v140, v141
	v_cvt_pk_bf16_f32 v141, v176, v177
	global_store_dwordx4 v[172:173], v[138:141], off
	v_cvt_f32_i32_e32 v49, v49
	v_cvt_f32_i32_e32 v48, v48
	v_pk_mul_f32 v[138:139], v[60:61], v[170:171] op_sel_hi:[1,0]
	v_pk_mul_f32 v[140:141], v[62:63], v[170:171] op_sel_hi:[1,0]
	v_pk_mul_f32 v[134:135], v[138:139], v[134:135]
	v_pk_mul_f32 v[136:137], v[140:141], v[136:137]
	v_pk_mul_f32 v[138:139], v[56:57], v[170:171] op_sel_hi:[1,0]
	v_pk_mul_f32 v[140:141], v[58:59], v[170:171] op_sel_hi:[1,0]
	v_cvt_f32_i32_e32 v51, v51
	v_pk_mul_f32 v[140:141], v[140:141], v[132:133]
	v_pk_mul_f32 v[132:133], v[138:139], v[130:131]
	v_cvt_pk_bf16_f32 v130, v134, v135
	v_cvt_pk_bf16_f32 v131, v136, v137
	v_pk_mul_f32 v[134:135], v[72:73], v[166:167] op_sel_hi:[1,0]
	v_cvt_pk_bf16_f32 v132, v132, v133
	v_cvt_pk_bf16_f32 v133, v140, v141
	global_store_dwordx4 v[172:173], v[130:133], off offset:256
	v_pk_mul_f32 v[136:137], v[74:75], v[166:167] op_sel_hi:[1,0]
	v_pk_mul_f32 v[126:127], v[134:135], v[126:127]
	v_or_b32_e32 v130, 16, v162
	v_mad_i64_i32 v[130:131], s[26:27], v130, s21, v[158:159]
	v_lshl_add_u64 v[132:133], v[130:131], 0, v[160:161]
	v_mov_b32_e32 v130, v178
	v_pk_mul_f32 v[128:129], v[136:137], v[128:129]
	v_pk_mul_f32 v[134:135], v[68:69], v[166:167] op_sel_hi:[1,0]
	v_pk_mul_f32 v[136:137], v[70:71], v[166:167] op_sel_hi:[1,0]
	v_cvt_f32_i32_e32 v50, v50
	v_pk_mul_f32 v[136:137], v[136:137], v[124:125]
	v_pk_mul_f32 v[124:125], v[134:135], v[122:123]
	v_cvt_pk_bf16_f32 v122, v126, v127
	v_cvt_pk_bf16_f32 v123, v128, v129
	v_cvt_f32_i32_e32 v45, v45
	v_cvt_pk_bf16_f32 v124, v124, v125
	v_cvt_pk_bf16_f32 v125, v136, v137
	global_store_dwordx4 v[132:133], v[122:125], off
	v_cvt_f32_i32_e32 v44, v44
	v_cvt_f32_i32_e32 v47, v47
	v_pk_mul_f32 v[122:123], v[60:61], v[166:167] op_sel_hi:[1,0]
	v_pk_mul_f32 v[124:125], v[62:63], v[166:167] op_sel_hi:[1,0]
	v_pk_mul_f32 v[118:119], v[122:123], v[118:119]
	v_pk_mul_f32 v[120:121], v[124:125], v[120:121]
	v_pk_mul_f32 v[122:123], v[56:57], v[166:167] op_sel_hi:[1,0]
	v_pk_mul_f32 v[124:125], v[58:59], v[166:167] op_sel_hi:[1,0]
	v_cvt_f32_i32_e32 v46, v46
	v_pk_mul_f32 v[124:125], v[124:125], v[116:117]
	v_pk_mul_f32 v[116:117], v[122:123], v[114:115]
	v_cvt_pk_bf16_f32 v114, v118, v119
	v_cvt_pk_bf16_f32 v115, v120, v121
	v_cvt_f32_i32_e32 v41, v41
	v_cvt_pk_bf16_f32 v116, v116, v117
	v_cvt_pk_bf16_f32 v117, v124, v125
	global_store_dwordx4 v[132:133], v[114:117], off offset:256
	v_cvt_f32_i32_e32 v40, v40
	v_cvt_f32_i32_e32 v43, v43
	v_or_b32_e32 v114, 32, v162
	v_mad_i64_i32 v[114:115], s[26:27], v114, s21, v[158:159]
	v_lshl_add_u64 v[116:117], v[114:115], 0, v[160:161]
	v_mov_b32_e32 v114, v179
	v_cvt_f32_i32_e32 v42, v42
	v_cvt_f32_i32_e32 v37, v37
	v_cvt_f32_i32_e32 v36, v36
	v_cvt_f32_i32_e32 v39, v39
	v_cvt_f32_i32_e32 v38, v38
	v_cvt_f32_i32_e32 v33, v33
	v_cvt_f32_i32_e32 v32, v32
	v_cvt_f32_i32_e32 v35, v35
	v_cvt_f32_i32_e32 v34, v34
	v_cvt_f32_i32_e32 v29, v29
	v_cvt_f32_i32_e32 v28, v28
	v_cvt_f32_i32_e32 v31, v31
	v_cvt_f32_i32_e32 v30, v30
	v_cvt_f32_i32_e32 v25, v25
	v_cvt_f32_i32_e32 v24, v24
	v_cvt_f32_i32_e32 v27, v27
	v_cvt_f32_i32_e32 v26, v26
	v_cvt_f32_i32_e32 v21, v21
	v_cvt_f32_i32_e32 v20, v20
	v_cvt_f32_i32_e32 v23, v23
	v_cvt_f32_i32_e32 v22, v22
	v_cvt_f32_i32_e32 v17, v17
	v_cvt_f32_i32_e32 v16, v16
	v_cvt_f32_i32_e32 v19, v19
	v_cvt_f32_i32_e32 v18, v18
	v_cvt_f32_i32_e32 v13, v13
	v_cvt_f32_i32_e32 v12, v12
	v_cvt_f32_i32_e32 v15, v15
	v_cvt_f32_i32_e32 v14, v14
	v_cvt_f32_i32_e32 v9, v9
	v_cvt_f32_i32_e32 v8, v8
	v_cvt_f32_i32_e32 v11, v11
	v_cvt_f32_i32_e32 v10, v10
	v_cvt_f32_i32_e32 v5, v5
	v_cvt_f32_i32_e32 v4, v4
	v_cvt_f32_i32_e32 v7, v7
	v_cvt_f32_i32_e32 v6, v6
	v_cvt_f32_i32_e32 v1, v1
	v_cvt_f32_i32_e32 v0, v0
	v_cvt_f32_i32_e32 v3, v3
	v_cvt_f32_i32_e32 v2, v2
	s_mov_b64 s[46:47], -1
	s_andn2_b64 vcc, exec, s[40:41]
	v_pk_mul_f32 v[118:119], v[72:73], v[130:131] op_sel_hi:[1,0]
	v_pk_mul_f32 v[120:121], v[74:75], v[130:131] op_sel_hi:[1,0]
	v_pk_mul_f32 v[110:111], v[118:119], v[110:111]
	v_pk_mul_f32 v[112:113], v[120:121], v[112:113]
	v_pk_mul_f32 v[118:119], v[68:69], v[130:131] op_sel_hi:[1,0]
	v_pk_mul_f32 v[120:121], v[70:71], v[130:131] op_sel_hi:[1,0]
	s_mov_b64 s[68:69], 0x4000
	v_pk_mul_f32 v[120:121], v[120:121], v[108:109]
	v_pk_mul_f32 v[108:109], v[118:119], v[106:107]
	v_cvt_pk_bf16_f32 v106, v110, v111
	v_cvt_pk_bf16_f32 v107, v112, v113
	s_mov_b64 s[64:65], 0xfff
	v_cvt_pk_bf16_f32 v108, v108, v109
	v_cvt_pk_bf16_f32 v109, v120, v121
	global_store_dwordx4 v[116:117], v[106:109], off
	s_nop 1
	v_pk_mul_f32 v[106:107], v[60:61], v[130:131] op_sel_hi:[1,0]
	v_pk_mul_f32 v[108:109], v[62:63], v[130:131] op_sel_hi:[1,0]
	v_pk_mul_f32 v[102:103], v[106:107], v[102:103]
	v_pk_mul_f32 v[104:105], v[108:109], v[104:105]
	v_pk_mul_f32 v[106:107], v[56:57], v[130:131] op_sel_hi:[1,0]
	v_pk_mul_f32 v[108:109], v[58:59], v[130:131] op_sel_hi:[1,0]
	s_nop 0
	v_pk_mul_f32 v[108:109], v[108:109], v[100:101]
	v_pk_mul_f32 v[100:101], v[106:107], v[98:99]
	v_cvt_pk_bf16_f32 v98, v102, v103
	v_cvt_pk_bf16_f32 v99, v104, v105
	v_pk_mul_f32 v[102:103], v[72:73], v[114:115] op_sel_hi:[1,0]
	v_cvt_pk_bf16_f32 v100, v100, v101
	v_cvt_pk_bf16_f32 v101, v108, v109
	global_store_dwordx4 v[116:117], v[98:101], off offset:256
	v_pk_mul_f32 v[104:105], v[74:75], v[114:115] op_sel_hi:[1,0]
	v_pk_mul_f32 v[92:93], v[102:103], v[92:93]
	v_or_b32_e32 v98, 48, v162
	v_mad_i64_i32 v[98:99], s[26:27], v98, s21, v[158:159]
	v_lshl_add_u64 v[100:101], v[98:99], 0, v[160:161]
	v_mov_b32_e32 v98, v180
	v_pk_mul_f32 v[94:95], v[104:105], v[94:95]
	v_pk_mul_f32 v[102:103], v[68:69], v[114:115] op_sel_hi:[1,0]
	v_pk_mul_f32 v[104:105], v[70:71], v[114:115] op_sel_hi:[1,0]
	s_nop 0
	v_pk_mul_f32 v[104:105], v[104:105], v[90:91]
	v_pk_mul_f32 v[90:91], v[102:103], v[88:89]
	v_cvt_pk_bf16_f32 v88, v92, v93
	v_cvt_pk_bf16_f32 v89, v94, v95
	s_nop 0
	v_cvt_pk_bf16_f32 v90, v90, v91
	v_cvt_pk_bf16_f32 v91, v104, v105
	global_store_dwordx4 v[100:101], v[88:91], off
	s_nop 1
	v_pk_mul_f32 v[88:89], v[60:61], v[114:115] op_sel_hi:[1,0]
	v_pk_mul_f32 v[90:91], v[62:63], v[114:115] op_sel_hi:[1,0]
	v_pk_mul_f32 v[84:85], v[88:89], v[84:85]
	v_pk_mul_f32 v[86:87], v[90:91], v[86:87]
	v_pk_mul_f32 v[88:89], v[56:57], v[114:115] op_sel_hi:[1,0]
	v_pk_mul_f32 v[90:91], v[58:59], v[114:115] op_sel_hi:[1,0]
	s_nop 0
	v_pk_mul_f32 v[90:91], v[90:91], v[82:83]
	v_pk_mul_f32 v[82:83], v[88:89], v[80:81]
	v_cvt_pk_bf16_f32 v80, v84, v85
	v_cvt_pk_bf16_f32 v81, v86, v87
	v_pk_mul_f32 v[84:85], v[72:73], v[98:99] op_sel_hi:[1,0]
	v_cvt_pk_bf16_f32 v82, v82, v83
	v_cvt_pk_bf16_f32 v83, v90, v91
	global_store_dwordx4 v[100:101], v[80:83], off offset:256
	v_pk_mul_f32 v[86:87], v[74:75], v[98:99] op_sel_hi:[1,0]
	v_pk_mul_f32 v[76:77], v[84:85], v[76:77]
	v_add_u32_e32 v80, 0x80, v162
	v_mad_i64_i32 v[80:81], s[26:27], v80, s21, v[158:159]
	v_lshl_add_u64 v[82:83], v[80:81], 0, v[160:161]
	v_mov_b32_e32 v80, v181
	v_pk_mul_f32 v[78:79], v[86:87], v[78:79]
	v_pk_mul_f32 v[84:85], v[68:69], v[98:99] op_sel_hi:[1,0]
	v_pk_mul_f32 v[86:87], v[70:71], v[98:99] op_sel_hi:[1,0]
	s_nop 0
	v_pk_mul_f32 v[86:87], v[86:87], v[66:67]
	v_pk_mul_f32 v[66:67], v[84:85], v[64:65]
	v_cvt_pk_bf16_f32 v64, v76, v77
	v_cvt_pk_bf16_f32 v65, v78, v79
	s_nop 0
	v_cvt_pk_bf16_f32 v66, v66, v67
	v_cvt_pk_bf16_f32 v67, v86, v87
	global_store_dwordx4 v[82:83], v[64:67], off
	s_nop 1
	v_pk_mul_f32 v[64:65], v[60:61], v[98:99] op_sel_hi:[1,0]
	v_pk_mul_f32 v[66:67], v[62:63], v[98:99] op_sel_hi:[1,0]
	v_pk_mul_f32 v[52:53], v[64:65], v[52:53]
	v_pk_mul_f32 v[54:55], v[66:67], v[54:55]
	v_pk_mul_f32 v[64:65], v[56:57], v[98:99] op_sel_hi:[1,0]
	v_pk_mul_f32 v[66:67], v[58:59], v[98:99] op_sel_hi:[1,0]
	s_nop 0
	v_pk_mul_f32 v[66:67], v[66:67], v[50:51]
	v_pk_mul_f32 v[50:51], v[64:65], v[48:49]
	v_cvt_pk_bf16_f32 v48, v52, v53
	v_cvt_pk_bf16_f32 v49, v54, v55
	v_pk_mul_f32 v[52:53], v[72:73], v[80:81] op_sel_hi:[1,0]
	v_cvt_pk_bf16_f32 v50, v50, v51
	v_cvt_pk_bf16_f32 v51, v66, v67
	global_store_dwordx4 v[82:83], v[48:51], off offset:256
	v_pk_mul_f32 v[54:55], v[74:75], v[80:81] op_sel_hi:[1,0]
	v_pk_mul_f32 v[44:45], v[52:53], v[44:45]
	v_add_u32_e32 v48, 0x90, v162
	v_mad_i64_i32 v[48:49], s[26:27], v48, s21, v[158:159]
	v_lshl_add_u64 v[50:51], v[48:49], 0, v[160:161]
	v_mov_b32_e32 v48, v182
	v_pk_mul_f32 v[46:47], v[54:55], v[46:47]
	v_pk_mul_f32 v[52:53], v[68:69], v[80:81] op_sel_hi:[1,0]
	v_pk_mul_f32 v[54:55], v[70:71], v[80:81] op_sel_hi:[1,0]
	s_nop 0
	v_pk_mul_f32 v[54:55], v[54:55], v[42:43]
	v_pk_mul_f32 v[42:43], v[52:53], v[40:41]
	v_cvt_pk_bf16_f32 v40, v44, v45
	v_cvt_pk_bf16_f32 v41, v46, v47
	s_nop 0
	v_cvt_pk_bf16_f32 v42, v42, v43
	v_cvt_pk_bf16_f32 v43, v54, v55
	global_store_dwordx4 v[50:51], v[40:43], off
	s_nop 1
	v_pk_mul_f32 v[40:41], v[60:61], v[80:81] op_sel_hi:[1,0]
	v_pk_mul_f32 v[42:43], v[62:63], v[80:81] op_sel_hi:[1,0]
	v_pk_mul_f32 v[36:37], v[40:41], v[36:37]
	v_pk_mul_f32 v[38:39], v[42:43], v[38:39]
	v_pk_mul_f32 v[40:41], v[56:57], v[80:81] op_sel_hi:[1,0]
	v_pk_mul_f32 v[42:43], v[58:59], v[80:81] op_sel_hi:[1,0]
	s_nop 0
	v_pk_mul_f32 v[42:43], v[42:43], v[34:35]
	v_pk_mul_f32 v[34:35], v[40:41], v[32:33]
	v_cvt_pk_bf16_f32 v32, v36, v37
	v_cvt_pk_bf16_f32 v33, v38, v39
	v_pk_mul_f32 v[36:37], v[72:73], v[48:49] op_sel_hi:[1,0]
	v_cvt_pk_bf16_f32 v34, v34, v35
	v_cvt_pk_bf16_f32 v35, v42, v43
	global_store_dwordx4 v[50:51], v[32:35], off offset:256
	v_pk_mul_f32 v[38:39], v[74:75], v[48:49] op_sel_hi:[1,0]
	v_pk_mul_f32 v[28:29], v[36:37], v[28:29]
	v_add_u32_e32 v32, 0xa0, v162
	v_mad_i64_i32 v[32:33], s[26:27], v32, s21, v[158:159]
	v_lshl_add_u64 v[34:35], v[32:33], 0, v[160:161]
	v_mov_b32_e32 v32, v183
	v_pk_mul_f32 v[30:31], v[38:39], v[30:31]
	v_pk_mul_f32 v[36:37], v[68:69], v[48:49] op_sel_hi:[1,0]
	v_pk_mul_f32 v[38:39], v[70:71], v[48:49] op_sel_hi:[1,0]
	s_nop 0
	v_pk_mul_f32 v[38:39], v[38:39], v[26:27]
	v_pk_mul_f32 v[26:27], v[36:37], v[24:25]
	v_cvt_pk_bf16_f32 v24, v28, v29
	v_cvt_pk_bf16_f32 v25, v30, v31
	s_nop 0
	v_cvt_pk_bf16_f32 v26, v26, v27
	v_cvt_pk_bf16_f32 v27, v38, v39
	global_store_dwordx4 v[34:35], v[24:27], off
	s_nop 1
	v_pk_mul_f32 v[24:25], v[60:61], v[48:49] op_sel_hi:[1,0]
	v_pk_mul_f32 v[26:27], v[62:63], v[48:49] op_sel_hi:[1,0]
	v_pk_mul_f32 v[20:21], v[24:25], v[20:21]
	v_pk_mul_f32 v[22:23], v[26:27], v[22:23]
	v_pk_mul_f32 v[24:25], v[56:57], v[48:49] op_sel_hi:[1,0]
	v_pk_mul_f32 v[26:27], v[58:59], v[48:49] op_sel_hi:[1,0]
	s_nop 0
	v_pk_mul_f32 v[26:27], v[26:27], v[18:19]
	v_pk_mul_f32 v[18:19], v[24:25], v[16:17]
	v_cvt_pk_bf16_f32 v16, v20, v21
	v_cvt_pk_bf16_f32 v17, v22, v23
	v_pk_mul_f32 v[20:21], v[74:75], v[32:33] op_sel_hi:[1,0]
	v_cvt_pk_bf16_f32 v18, v18, v19
	v_cvt_pk_bf16_f32 v19, v26, v27
	global_store_dwordx4 v[34:35], v[16:19], off offset:256
	v_pk_mul_f32 v[14:15], v[20:21], v[14:15]
	v_pk_mul_f32 v[20:21], v[70:71], v[32:33] op_sel_hi:[1,0]
	v_pk_mul_f32 v[18:19], v[72:73], v[32:33] op_sel_hi:[1,0]
	v_add_u32_e32 v16, 0xb0, v162
	v_pk_mul_f32 v[12:13], v[18:19], v[12:13]
	v_pk_mul_f32 v[18:19], v[68:69], v[32:33] op_sel_hi:[1,0]
	v_mad_i64_i32 v[16:17], s[26:27], v16, s21, v[158:159]
	v_pk_mul_f32 v[20:21], v[20:21], v[10:11]
	v_pk_mul_f32 v[10:11], v[18:19], v[8:9]
	v_lshl_add_u64 v[16:17], v[16:17], 0, v[160:161]
	v_cvt_pk_bf16_f32 v8, v12, v13
	v_cvt_pk_bf16_f32 v9, v14, v15
	v_cvt_pk_bf16_f32 v10, v10, v11
	v_cvt_pk_bf16_f32 v11, v20, v21
	global_store_dwordx4 v[16:17], v[8:11], off
	s_nop 1
	v_pk_mul_f32 v[8:9], v[60:61], v[32:33] op_sel_hi:[1,0]
	v_pk_mul_f32 v[10:11], v[62:63], v[32:33] op_sel_hi:[1,0]
	v_pk_mul_f32 v[4:5], v[8:9], v[4:5]
	v_pk_mul_f32 v[6:7], v[10:11], v[6:7]
	v_pk_mul_f32 v[8:9], v[56:57], v[32:33] op_sel_hi:[1,0]
	v_pk_mul_f32 v[10:11], v[58:59], v[32:33] op_sel_hi:[1,0]
	s_nop 0
	v_pk_mul_f32 v[10:11], v[10:11], v[2:3]
	v_pk_mul_f32 v[2:3], v[8:9], v[0:1]
	v_cvt_pk_bf16_f32 v0, v4, v5
	v_cvt_pk_bf16_f32 v1, v6, v7
	s_nop 0
	v_cvt_pk_bf16_f32 v2, v2, v3
	v_cvt_pk_bf16_f32 v3, v10, v11
	global_store_dwordx4 v[16:17], v[0:3], off offset:256
	s_cbranch_vccnz .LBB0_305
	s_andn2_b64 vcc, exec, s[6:7]
	s_cbranch_vccnz .LBB0_304
	s_barrier
	s_branch .LBB0_304
